# grid.sync() after the prologue replaced by a ready-word wait + the kernel's own XCD grid barrier (block 0 zeroes barrier words, publishes ready word)
# speedup vs baseline: 1.0446x; 1.0167x over previous
; __device__ __forceinline__ ArgP argp() { ArgP p = (ArgP)__builtin_amdgcn_kernarg_segment_ptr(); asm volatile("" : "+s"(p)); return p; }
; __global__ void __launch_bounds__(NTHREADS, 2) fwd_megakernel(Args a_) {
;     ...
;     if (IN(0)) { p0_prologue(argp(), lds, G); __syncthreads(); }
;     grid.sync();
;     XcdBarrier xbar = xcd_barrier_post(ctl, xst);
.LBB0_101:
	s_or_b64 exec, exec, s[0:1]
	v_lshrrev_b32_e32 v2, 20, v0
	v_lshrrev_b32_e32 v0, 10, v0
	v_or_b32_e32 v0, v0, v2
	s_movk_i32 s0, 0x3ff
	v_and_or_b32 v0, v0, s0, v193
	v_cmp_eq_u32_e32 vcc, 0, v0
	s_barrier
	s_and_saveexec_b64 s[0:1], vcc
	s_cbranch_execz .LBB0_111
	v_readlane_b32 s2, v254, 2
	v_readlane_b32 s3, v254, 3
	s_add_u32 s2, s2, 0x184000
	s_addc_u32 s3, s3, 0
	v_mov_b32_e32 v0, 0
	s_mov_b32 s4, 0
.Lgs_poll:
	global_load_dword v2, v0, s[2:3] sc0 sc1
	s_waitcnt vmcnt(0)
	v_readfirstlane_b32 s5, v2
	s_cmp_eq_u32 s5, 0x5afec0de
	s_cbranch_scc1 .LBB0_111
	s_sleep 2
	s_add_u32 s4, s4, 1
	s_cmp_lt_u32 s4, 0x100000
	s_cbranch_scc1 .Lgs_poll

;     __host__ __device__ void init(int M, int N, int K, long L_) { base.init(M, N, 1, 0, K); L = L_; }
;     __host__ __device__ void init(int M0, int Mtot, int N, int K, int G_, int c_) { base.init(M0, N, G_, c_, K); nrest = ((Mtot - M0) / BM) * NN * S; nkp = (K / BK) / S; G = G_; c = c_; }
; __device__ __forceinline__ int bxl() { int b = blockIdx.x; asm volatile("" : "+s"(b)); return b; }
; __global__ void __launch_bounds__(NTHREADS, 2) fwd_megakernel(Args a_) {
;     ...
;     XcdBarrier xbar = xcd_barrier_post(ctl, xst);
; #pragma unroll 1
;     for (int l = 0; l < DEPTH; ++l) {
;         const int pb = 1 + 8 * l;
;         const unsigned char* wl = ws + WS_W + (size_t)l * W_LAYER;
;         if (PHON(0) && IN(pb + 0)) {
;             pg8::Gemm g{XN, (const bf16*)(wl + W_IN), MP, NIN, DM}; pg8::StaticOrder S; S.init(MP, NIN, G, bxl(), DM);
.LBB0_114:
	s_or_b64 exec, exec, s[0:1]
	v_readlane_b32 s4, v254, 2
	v_readlane_b32 s5, v254, 3
	s_add_u32 s0, s4, 0x5300000
	v_writelane_b32 v254, s0, 15
	s_addc_u32 s0, s5, 0
	v_writelane_b32 v254, s0, 16
	s_add_u32 s0, s4, 0x7580000
	s_addc_u32 s1, s5, 0
	v_writelane_b32 v254, s0, 17
	v_mov_b32_e32 v189, 0
	v_mov_b32_e32 v207, 0x358637bd
	v_writelane_b32 v254, s1, 18
	s_add_u32 s0, s4, 0xba80000
	v_writelane_b32 v254, s0, 19
	s_addc_u32 s0, s5, 0
	v_writelane_b32 v254, s0, 20
	s_add_u32 s0, s4, 0x16700000
	s_addc_u32 s1, s5, 0
	v_writelane_b32 v254, s0, 21
	v_mbcnt_hi_u32_b32 v208, -1, v1
	s_nop 0
	v_writelane_b32 v254, s1, 22
	s_add_u32 s0, s4, 0xdd00000
	v_writelane_b32 v254, s0, 23
	s_addc_u32 s0, s5, 0
	v_writelane_b32 v254, s0, 24
	s_add_u32 s0, s4, 0x200000
	v_writelane_b32 v254, s0, 25
	s_addc_u32 s0, s5, 0
	v_writelane_b32 v254, s0, 26
	s_nop 0
	v_readlane_b32 s6, v254, 0
	s_ashr_i32 s0, s6, 31
	v_readlane_b32 s7, v254, 1
	v_writelane_b32 v254, s0, 27
	s_nop 0
	v_readlane_b32 s1, v254, 8
	s_cmp_lt_i32 s1, 64
	s_cselect_b64 s[2:3], -1, 0
	s_cmp_gt_i32 s6, 64
	v_writelane_b32 v254, s2, 28
	s_cselect_b32 s0, 64, 0
	s_nop 0
	v_writelane_b32 v254, s3, 29
	s_sub_i32 s2, s6, s0
	s_cmp_ge_i32 s1, s0
	s_cselect_b64 s[8:9], -1, 0
	v_writelane_b32 v254, s8, 30
	s_sub_i32 s1, s1, s0
	s_lshl_b32 s0, s1, 3
	v_writelane_b32 v254, s9, 31
	v_writelane_b32 v254, s0, 32
	s_lshl_b32 s0, s2, 3
	v_writelane_b32 v254, s2, 33
	s_cmpk_lt_i32 s1, 0x400
	v_writelane_b32 v254, s0, 34
	s_cselect_b64 s[2:3], -1, 0
	s_add_i32 s0, s1, 0x54
	v_writelane_b32 v254, s2, 35
	s_cmp_lt_i32 s1, 20
	s_cselect_b32 s0, s1, s0
	v_writelane_b32 v254, s3, 36
	v_writelane_b32 v254, s1, 37
	s_max_i32 s1, s0, 0
	s_cmpk_lt_i32 s0, 0x114
	s_cselect_b32 s1, s1, 0
	s_and_b32 s2, s1, 7
	s_mul_i32 s3, s2, 34
	s_add_i32 s3, s3, 4
	s_lshr_b32 s1, s1, 3
	s_cmpk_lt_u32 s0, 0x114
	s_cselect_b64 s[8:9], -1, 0
	v_writelane_b32 v254, s8, 38
	s_add_u32 s0, s4, 0x14480000
	s_nop 0
	v_writelane_b32 v254, s9, 39
	v_writelane_b32 v254, s0, 40
	s_addc_u32 s0, s5, 0
	s_add_u32 s8, s4, 0x1ac00000
	v_writelane_b32 v254, s0, 41
	s_addc_u32 s9, s5, 0
	v_writelane_b32 v254, s8, 42
	s_add_u32 s4, s4, 0x18980000
	s_addc_u32 s5, s5, 0
	v_writelane_b32 v254, s9, 43
	v_writelane_b32 v254, s4, 44
	s_add_i32 s0, s26, 0xfffffcc0
	s_cmp_lt_u32 s2, 4
	v_writelane_b32 v254, s5, 45
	s_mul_i32 s2, s2, 35
	v_writelane_b32 v254, s0, 46
	s_cselect_b32 s0, s2, s3
	s_add_i32 s0, s0, s1
	s_lshr_b32 s2, s0, 2
	s_and_b32 s1, s2, 0x1ffffff8
	s_sub_i32 s3, 0x45, s1
	s_min_i32 s3, s3, 8
	s_abs_i32 s4, s3
	v_cvt_f32_u32_e32 v0, s4
	s_mul_i32 s5, s7, s6
	v_readlane_b32 s6, v254, 4
	v_readlane_b32 s7, v254, 5
	v_rcp_iflag_f32_e32 v0, v0
	s_load_dword s6, s[6:7], 0x98
	v_mul_f32_e32 v0, 0x4f7ffffe, v0
	v_cvt_u32_f32_e32 v0, v0
	s_waitcnt lgkmcnt(0)
	s_mul_i32 s5, s5, s6
	s_sub_i32 s6, 0, s4
	v_writelane_b32 v254, s5, 47
	v_readfirstlane_b32 s7, v0
	s_mul_i32 s6, s6, s7
	s_mul_hi_u32 s6, s7, s6
	s_and_b32 s5, s0, 31
	s_add_i32 s7, s7, s6
	s_mul_hi_u32 s6, s5, s7
	s_mul_i32 s7, s6, s4
	s_sub_i32 s7, s5, s7
	s_ashr_i32 s0, s3, 31
	s_add_i32 s8, s6, 1
	s_sub_i32 s9, s7, s4
	s_cmp_ge_u32 s7, s4
	s_cselect_b32 s6, s8, s6
	s_cselect_b32 s7, s9, s7
	s_add_i32 s8, s6, 1
	s_cmp_ge_u32 s7, s4
	s_cselect_b32 s4, s8, s6
	s_xor_b32 s4, s4, s0
	s_sub_i32 s0, s4, s0
	s_mul_i32 s3, s0, s3
	s_sub_i32 s4, s5, s3
	s_mov_b32 s7, 0
	s_add_i32 s6, s1, s4
	s_lshl_b64 s[8:9], s[6:7], 19
	v_writelane_b32 v254, s8, 48
	s_ashr_i32 s1, s0, 31
	s_lshl_b32 s4, s6, 8
	v_writelane_b32 v254, s9, 49
	s_lshl_b64 s[8:9], s[0:1], 19
	v_writelane_b32 v254, s8, 50
	s_lshl_b64 s[0:1], s[0:1], 8
	s_ashr_i32 s27, s26, 31
	v_writelane_b32 v254, s9, 51
	v_writelane_b32 v254, s4, 52
	v_writelane_b32 v254, s0, 53
	s_nop 1
	v_writelane_b32 v254, s1, 54
	v_writelane_b32 v254, s26, 55
	s_and_b32 s0, s2, 0x7fffff8
	s_add_i32 s5, s5, s0
	v_writelane_b32 v254, s27, 56
	s_sub_i32 s6, s5, s3
	v_readlane_b32 s0, v254, 9
	s_sub_i32 s0, s26, s0
	s_addk_i32 s0, 0x3fff
	v_writelane_b32 v254, s0, 57
	s_add_i32 s0, 0, 0x23fc0
	v_writelane_b32 v254, s0, 58
	s_add_i32 s0, 0, 0x23fc4
	v_writelane_b32 v254, s0, 59
	s_add_i32 s0, 0, 0x19800
	v_writelane_b32 v254, s0, 60
	s_add_i32 s0, 0, 0x11000
	v_writelane_b32 v254, s0, 6
	s_add_i32 s0, 0, 0x22000
	v_writelane_b32 v254, s0, 61
	s_lshl_b64 s[0:1], s[6:7], 19
	v_writelane_b32 v254, s0, 62
	s_nop 1
	v_writelane_b32 v254, s1, 63
	s_lshl_b64 s[0:1], s[26:27], 11
	v_writelane_b32 v255, s0, 0
	s_nop 1
	v_writelane_b32 v255, s1, 1
	s_mov_b64 s[0:1], -1
	v_writelane_b32 v255, s0, 2
	s_nop 1
	v_writelane_b32 v255, s1, 3
	s_mov_b32 s1, s7
	v_writelane_b32 v255, s0, 4
	s_nop 1
	v_writelane_b32 v255, s1, 5
	s_mov_b32 s0, s7
	v_writelane_b32 v255, s0, 6
	s_nop 1
	v_writelane_b32 v255, s1, 7
	s_mov_b32 s0, 1
	s_nop 1
	v_writelane_b32 v255, s0, 53
	s_branch .LBB0_264

; #define LAS __attribute__((address_space(3)))
; __device__ __forceinline__ void mixer_phase(ArgP a, LAS unsigned char* lds, int layer, int G) {
;     unsigned char* ws = a->ws;
;     bf16* P = (bf16*)(ws + WS_P); const size_t BS = ROWBUF / 2;
;     bf16* Qb = P; const bf16* Kb = P + BS; const bf16* Vb = P + 2 * BS; const bf16* Gb = P + 3 * BS; bf16* BGb = P + 4 * BS; const bf16* Ub = P + 5 * BS;
;     const f32x2* tab = (const f32x2*)(ws + WS_TAB);
;     const int wgi = blockIdx.x;
;     for (int ci = wgi; ci < NB * NH; ci += G) {
;         const int b = ci >> 3, h = ci & 7;
;     ...
;         ret_chain<false>(lds, b, h, Qb, Kb, Vb, Gb, tab, a->out + O_SRP + ((size_t)(layer * NB + b) * NH + h) * HD * HD);
;     ...
;         ret_chain<true>(lds, b, h, Qb, Kb, Vb, Gb, tab, a->out + O_SRP + ((size_t)(layer * NB + b) * NH + h) * HD * HD);
;     }
;     const int first_other = (G > NB * NH) ? NB * NH : 0, n_other = G - first_other;
;     if (wgi >= first_other) {
;         const int oi = wgi - first_other;
; __device__ __forceinline__ void xcd_barrier(const XcdBarrier& b) {
;     asm volatile("s_waitcnt vmcnt(0)" ::: "memory");
;     __syncthreads();
;     if (threadIdx.x == 0) {
;         unsigned* bar = b.bar;
;         __builtin_amdgcn_s_waitcnt(0);
;         unsigned nloc = b.st[0], nx = b.st[1];
;         if (nloc == 0u) { xcd_barrier_complete(bar, b.x, nloc, nx); b.st[0] = nloc; b.st[1] = nx; }
;         const unsigned old = xb_add(&bar[XB_XSUB(b.x)], 1u);
;         const unsigned gen = old / nloc;
;         if (old + 1u == (gen + 1u) * nloc) {
;             __builtin_amdgcn_fence(__ATOMIC_RELEASE, "agent");
;             asm volatile("s_waitcnt vmcnt(0)" ::: "memory");
;             const unsigned og = xb_add(&bar[XB_TOP], 1u);
;             const unsigned tg = og / nx;
;             if (og + 1u == (tg + 1u) * nx) xb_add(&bar[XB_TOPGEN], 1u);
;             else XB_SPIN(xb_ld(&bar[XB_TOPGEN]) == tg, bar);
;             __builtin_amdgcn_fence(__ATOMIC_ACQUIRE, "agent");
;             xb_add(&bar[XB_XGEN(b.x)], 1u);
;             asm volatile("s_waitcnt vmcnt(0)" ::: "memory");
;         } else {
;             XB_SPIN(xb_ld(&bar[XB_XGEN(b.x)]) == gen, bar);
;             __builtin_amdgcn_fence(__ATOMIC_ACQUIRE, "agent");
;             asm volatile("s_waitcnt vmcnt(0)" ::: "memory");
;         }
;     }
;     __syncthreads();
; }
.LBB0_308:
	s_or_b64 exec, exec, s[2:3]
	v_readlane_b32 s0, v255, 2
	v_readlane_b32 s1, v255, 3
	s_xor_b64 s[0:1], s[0:1], -1
	v_writelane_b32 v255, s0, 11
	s_waitcnt lgkmcnt(0)
	s_barrier
	v_writelane_b32 v255, s1, 12
	v_readlane_b32 s0, v255, 53
	s_nop 1
	s_cmp_eq_u32 s0, 0
	s_cbranch_scc1 .Lgs_cont
	s_mov_b32 s0, 0
	s_nop 1
	v_writelane_b32 v255, s0, 53
	v_readlane_b32 s0, v254, 8
	s_nop 1
	s_cmp_lg_u32 s0, 0
	s_cbranch_scc1 .LBB0_118
	v_readlane_b32 s0, v254, 2
	v_readlane_b32 s1, v254, 3
	s_add_u32 s0, s0, 0x184000
	s_addc_u32 s1, s1, 0
	v_mov_b32_e32 v0, 0
	v_mov_b32_e32 v1, 0
	global_store_dword v0, v1, s[0:1] sc0 sc1
	s_branch .LBB0_118
.Lgs_cont:
	v_readlane_b32 s0, v254, 4
	v_readlane_b32 s1, v254, 5
	s_nop 0
	v_writelane_b32 v255, s0, 13
	s_nop 1
	v_writelane_b32 v255, s1, 14
	s_load_dwordx2 s[0:1], s[0:1], 0x80
	s_waitcnt lgkmcnt(0)
	s_add_u32 s2, s0, 0xba80000
	s_addc_u32 s3, s1, 0
	s_add_u32 s40, s0, 0xdd00000
	s_addc_u32 s41, s1, 0
	s_add_u32 s42, s0, 0xff80000
	s_addc_u32 s43, s1, 0
	s_add_u32 s4, s0, 0x12200000
	v_writelane_b32 v255, s0, 15
	s_addc_u32 s5, s1, 0
	s_nop 0
	v_writelane_b32 v255, s1, 16
	v_writelane_b32 v255, s4, 17
	v_readlane_b32 s0, v254, 28
	v_readlane_b32 s1, v254, 29
	v_writelane_b32 v255, s5, 18
	s_andn2_b64 vcc, exec, s[0:1]
	v_readlane_b32 s0, v255, 4
	v_readlane_b32 s4, v255, 6
	v_readlane_b32 s1, v255, 5
	v_readlane_b32 s5, v255, 7
	s_mov_b32 s5, s1
	v_writelane_b32 v255, s4, 6
	s_nop 1
	v_writelane_b32 v255, s5, 7
	s_cbranch_vccnz .LBB0_465
	v_readlane_b32 s0, v255, 13
	v_readlane_b32 s1, v255, 14
	s_load_dwordx2 s[0:1], s[0:1], 0x78
	s_waitcnt lgkmcnt(0)
	s_add_u32 s0, s0, 0x4400000
	v_writelane_b32 v255, s0, 19
	s_addc_u32 s0, s1, 0
	v_writelane_b32 v255, s0, 20
	s_nop 0
	v_readlane_b32 s0, v255, 6
	s_lshl_b32 s0, s0, 3
	v_readlane_b32 s1, v255, 7
	v_writelane_b32 v255, s0, 21
	v_readlane_b32 s0, v254, 8
	s_mov_b32 s7, s0
	s_branch .LBB0_311

; #define LAS __attribute__((address_space(3)))
; __global__ void __launch_bounds__(NTHREADS, 2) fwd_megakernel(Args a_) {
;     ...
;     unsigned* ctl = (unsigned*)(ws + WS_CTL);
;     if (blockIdx.x == 0) for (int i = threadIdx.x; i < 4096; i += NTHREADS) __hip_atomic_store(ctl + i, 0u, __ATOMIC_RELAXED, __HIP_MEMORY_SCOPE_AGENT);
;     volatile LAS unsigned* xst = (volatile LAS unsigned*)(lds + LDS_BYTES - 64);
;     if (threadIdx.x < 2) xst[threadIdx.x] = 0u;
;     __syncthreads();
.LBB0_1381:
	v_add_u32_e32 v1, 0x200, v1
	v_cmp_lt_u32_e32 vcc, s6, v1
	global_store_dword v[4:5], v3, off sc1
	s_or_b64 s[0:1], vcc, s[0:1]
	v_lshl_add_u64 v[4:5], v[4:5], 0, s[4:5]
	s_andn2_b64 exec, exec, s[0:1]
	s_cbranch_execnz .LBB0_1381
	s_or_b64 exec, exec, s[0:1]
	s_waitcnt vmcnt(0)
	s_barrier
	v_readlane_b32 s0, v254, 2
	v_readlane_b32 s1, v254, 3
	s_add_u32 s0, s0, 0x184000
	s_addc_u32 s1, s1, 0
	v_mov_b32_e32 v1, 0x5afec0de
	v_mov_b32_e32 v2, 0
	global_store_dword v2, v1, s[0:1] sc0 sc1
	v_cmp_gt_u32_e32 vcc, 2, v193
	s_and_saveexec_b64 s[0:1], vcc
	s_cbranch_execz .LBB0_1385
	s_getpc_b64 s[98:99]
